# mix1 load balance: workgroup halves < 256 (which run a second q_tile) take 3 ssm1 items, halves >= 256 take 5 (stride-256 partition of the 2048 items)
# speedup vs baseline: 1.0114x; 1.0061x over previous
; DI int tidx() { int t = threadIdx.x & 255; asm volatile("" : "+v"(t)); return t; }
; DI int vbid() { return (int)blockIdx.x * 2 + half_(); }
; DI int vgrid() { return (int)gridDim.x * 2; }
; DI void ssm_stage_u(PREF p, int b, int c, int gq, float* uS) {
;   const int tid = tidx();
;   int row = tid >> 2, cc = (tid & 3) * 16;
;   const u16* src = p.hb + (size_t)(b * S_ + c * 64 + row) * HW + OFF_U + gq * 64 + cc;
;   float f[16];
;   unpack8(*(const u32x4*)src, f); unpack8(*(const u32x4*)(src + 8), f + 8);
; #pragma unroll
;   for (int j = 0; j < 4; ++j) *(float4*)(uS + row * 64 + cc + 4 * j) = make_float4(f[4 * j], f[4 * j + 1], f[4 * j + 2], f[4 * j + 3]);
; }
; DI void ssm1_item(PREF p, int l, int item, unsigned char* ldsb) {
;   const int gq = item & 3, c = (item >> 2) & 63, b = item >> 8;
;   const int tid = tidx(), w = tid >> 6, lane = tid & 63;
;   const int g = gq * 4 + w;
;   float* uS = (float*)ldsb;
;   __syncthreads();
;   ssm_stage_u(p, b, c, gq, uS);
;   __syncthreads();
;   const size_t pi = (size_t)(l * 16 + g) * 64 + lane;
;   float bre[16], bim[16];
; #pragma unroll
;   for (int j = 0; j < 16; ++j) { bre[j] = p.bbre[pi * 16 + j]; bim[j] = p.bbim[pi * 16 + j]; }
; DI void phase_mix1(PREF p, int l, unsigned char* ldsb) {
;     ...
;   for (int it = vbid(); it < 768; it += vgrid()) q_tile(p, l, it, ldsb);
;   for (int it = vbid(); it < 1024; it += vgrid()) conv_item(p, l, it, ldsb);
;   for (int it = vbid(); it < 2048; it += vgrid()) ssm1_item(p, l, it, ldsb);
.LBB0_420:
	v_readfirstlane_b32 s0, v168
	s_lshr_b32 s0, s0, 8
	s_add_i32 s12, s0, s70
	s_movk_i32 s98, 0x7ff
	s_mov_b32 s99, s71
	s_cmpk_lg_u32 s71, 0x200
	s_cbranch_scc1 .Lmy_s1bal
	s_movk_i32 s99, 0x100
	s_cmpk_lt_u32 s12, 0x100
	s_cbranch_scc1 .Lmy_s1low
	s_addk_i32 s12, 0x200
	s_branch .Lmy_s1bal
.Lmy_s1low:
	s_movk_i32 s98, 0x2ff
.Lmy_s1bal:
	v_readlane_b32 s18, v254, 46
	s_cmp_gt_i32 s12, s98
	v_readlane_b32 s19, v254, 47
	s_cbranch_scc1 .LBB0_425
	s_load_dwordx4 s[8:11], s[18:19], 0x108
	s_lshl_b32 s13, s56, 4
.LBB0_422:
	s_ashr_i32 s14, s12, 8
	v_mov_b32_e32 v25, v169
	v_mov_b32_e32 v0, v169
	s_lshl_b32 s1, s12, 4
	s_waitcnt lgkmcnt(0)
	s_barrier
	s_lshl_b32 s0, s14, 12
	s_and_b32 s15, s1, 0xfc0
	v_ashrrev_i32_e32 v10, 2, v0
	v_lshlrev_b32_e32 v0, 4, v0
	s_or_b32 s0, s15, s0
	v_and_b32_e32 v11, 48, v0
	v_add_u32_e32 v0, s0, v10
	s_load_dwordx2 s[0:1], s[18:19], 0x140
	s_and_b32 s16, s12, 3
	s_lshl_b32 s52, s16, 7
	v_ashrrev_i32_e32 v12, 6, v25
	v_lshl_add_u32 v41, s16, 2, v12
	s_waitcnt lgkmcnt(0)
	v_mov_b64_e32 v[2:3], s[0:1]
	v_mad_i64_i32 v[2:3], s[0:1], v0, s60, v[2:3]
	v_lshl_add_u64 v[2:3], v[2:3], 0, s[52:53]
	v_lshlrev_b32_e32 v0, 1, v11
	v_lshl_add_u64 v[6:7], v[2:3], 0, v[0:1]
	global_load_dwordx4 v[2:5], v[6:7], off offset:2880
	s_nop 0
	global_load_dwordx4 v[6:9], v[6:7], off offset:2896
	v_lshlrev_b32_e32 v12, 8, v10
	v_lshlrev_b32_e32 v11, 2, v11
	v_add_u32_e32 v10, s13, v41
	s_load_dwordx2 s[0:1], s[18:19], 0x118
	v_add3_u32 v24, s33, v12, v11
	v_ashrrev_i32_e32 v11, 31, v10
	v_and_b32_e32 v0, 63, v25
	v_lshlrev_b64 v[22:23], 6, v[10:11]
	v_or_b32_e32 v22, v22, v0
	v_lshlrev_b64 v[10:11], 6, v[22:23]
	v_lshl_add_u64 v[18:19], s[10:11], 0, v[10:11]
	s_waitcnt lgkmcnt(0)
	v_lshl_add_u64 v[20:21], s[0:1], 0, v[10:11]
	v_lshl_add_u64 v[22:23], v[22:23], 3, s[8:9]
	v_and_b32_e32 v25, 0xffffffc0, v25
	s_mov_b32 s16, 0
	v_add_u32_e32 v42, s33, v25
	v_mov_b32_e32 v40, 0
	s_waitcnt vmcnt(1)
	v_lshlrev_b32_e32 v10, 16, v2
	v_and_b32_e32 v11, 0xffff0000, v2
	v_lshlrev_b32_e32 v12, 16, v3
	v_and_b32_e32 v13, 0xffff0000, v3
	v_lshlrev_b32_e32 v2, 16, v4
	v_and_b32_e32 v3, 0xffff0000, v4
	v_lshlrev_b32_e32 v4, 16, v5
	v_and_b32_e32 v5, 0xffff0000, v5
	s_waitcnt vmcnt(0)
	v_lshlrev_b32_e32 v14, 16, v6
	v_and_b32_e32 v15, 0xffff0000, v6
	v_lshlrev_b32_e32 v16, 16, v7
	v_and_b32_e32 v17, 0xffff0000, v7
	v_lshlrev_b32_e32 v6, 16, v8
	v_and_b32_e32 v7, 0xffff0000, v8
	v_lshlrev_b32_e32 v8, 16, v9
	v_and_b32_e32 v9, 0xffff0000, v9
	ds_write_b128 v24, v[10:13]
	ds_write_b128 v24, v[2:5] offset:16
	ds_write_b128 v24, v[14:17] offset:32
	ds_write_b128 v24, v[6:9] offset:48
	s_waitcnt lgkmcnt(0)
	s_barrier
	global_load_dwordx4 v[2:5], v[18:19], off offset:16
	global_load_dwordx4 v[6:9], v[20:21], off offset:16
	global_load_dwordx4 v[30:33], v[18:19], off offset:32
	global_load_dwordx4 v[10:13], v[20:21], off offset:32
	global_load_dwordx4 v[34:37], v[18:19], off offset:48
	global_load_dwordx4 v[14:17], v[20:21], off offset:48
	global_load_dwordx4 v[44:47], v[18:19], off
	s_nop 0
	global_load_dwordx4 v[18:21], v[20:21], off
	v_mov_b32_e32 v24, 0
	global_load_dwordx2 v[22:23], v[22:23], off
	s_waitcnt vmcnt(8)
	v_mov_b32_e32 v26, v5
	s_waitcnt vmcnt(7)
	v_mov_b32_e32 v27, v9
	s_waitcnt vmcnt(6)
	v_mov_b32_e32 v28, v30
	s_waitcnt vmcnt(5)
	v_mov_b32_e32 v29, v10
	v_mov_b32_e32 v10, v31
	v_mov_b32_e32 v30, v32
	v_mov_b32_e32 v31, v12
	v_mov_b32_e32 v12, v33
	s_waitcnt vmcnt(4)
	v_mov_b32_e32 v32, v34
	s_waitcnt vmcnt(3)
	v_mov_b32_e32 v33, v14
	v_mov_b32_e32 v14, v35
	v_mov_b32_e32 v34, v36
	v_mov_b32_e32 v35, v16
	v_mov_b32_e32 v16, v37
	v_mov_b32_e32 v5, v8
	s_waitcnt vmcnt(2)
	v_mov_b32_e32 v8, v44
	s_waitcnt vmcnt(1)
	v_mov_b32_e32 v9, v18
	v_mov_b32_e32 v18, v45
	v_mov_b32_e32 v36, v46
	v_mov_b32_e32 v37, v20
	v_mov_b32_e32 v20, v47
	v_mov_b32_e32 v38, v2
	v_mov_b32_e32 v39, v6
	v_mov_b32_e32 v6, v3
	s_waitcnt vmcnt(0)
	v_pk_mov_b32 v[2:3], v[22:23], v[22:23] op_sel:[1,0]
	v_mov_b32_e32 v25, 0
	v_permlane32_swap_b32 v8, v18
	v_permlane32_swap_b32 v9, v19
	v_permlane32_swap_b32 v36, v20
	v_permlane32_swap_b32 v37, v21
	v_permlane32_swap_b32 v38, v6
	v_permlane32_swap_b32 v39, v7
	v_permlane32_swap_b32 v4, v26
	v_permlane32_swap_b32 v5, v27
	v_permlane32_swap_b32 v28, v10
	v_permlane32_swap_b32 v29, v11
	v_permlane32_swap_b32 v30, v12
	v_permlane32_swap_b32 v31, v13
	v_permlane32_swap_b32 v32, v14
	v_permlane32_swap_b32 v33, v15
	v_permlane32_swap_b32 v34, v16
	v_permlane32_swap_b32 v35, v17
	v_bfe_u32 v128, v172, 2, 1
	v_bfe_u32 v129, v172, 3, 2
	v_and_b32_e32 v130, 3, v172
	v_lshlrev_b32_e32 v128, 4, v128
	v_lshl_add_u32 v128, v129, 2, v128
	v_add_u32_e32 v128, v128, v130
	v_lshlrev_b32_e32 v128, 8, v128
	v_lshrrev_b32_e32 v129, 5, v172
	v_lshl_add_u32 v126, v129, 2, v128
	v_add_u32_e32 v127, v42, v126
	ds_read2_b32 v[118:119], v127 offset0:0 offset1:2
	ds_read2_b32 v[120:121], v127 offset0:4 offset1:6
	ds_read2_b32 v[122:123], v127 offset0:8 offset1:10
	ds_read2_b32 v[124:125], v127 offset0:12 offset1:14
	s_waitcnt lgkmcnt(0)
; DI void ssm1_item(PREF p, int l, int item, unsigned char* ldsb) {
;     ...
;   for (int t = 0; t < 64; ++t) SSM_STEP(t)
	v_mfma_f32_32x32x2_f32 v[184:199], v118, v8, 0
	v_mfma_f32_32x32x2_f32 v[200:215], v118, v9, 0
	v_mfma_f32_32x32x2_f32 v[216:231], v118, v18, 0
	v_mfma_f32_32x32x2_f32 v[232:247], v118, v19, 0
	v_mfma_f32_32x32x2_f32 v[184:199], v119, v36, v[184:199]
	v_mfma_f32_32x32x2_f32 v[200:215], v119, v37, v[200:215]
	v_mfma_f32_32x32x2_f32 v[216:231], v119, v20, v[216:231]
	v_mfma_f32_32x32x2_f32 v[232:247], v119, v21, v[232:247]
	v_mfma_f32_32x32x2_f32 v[184:199], v120, v38, v[184:199]
	v_mfma_f32_32x32x2_f32 v[200:215], v120, v39, v[200:215]
	v_mfma_f32_32x32x2_f32 v[216:231], v120, v6, v[216:231]
	v_mfma_f32_32x32x2_f32 v[232:247], v120, v7, v[232:247]
	v_mfma_f32_32x32x2_f32 v[184:199], v121, v4, v[184:199]
	v_mfma_f32_32x32x2_f32 v[200:215], v121, v5, v[200:215]
	v_mfma_f32_32x32x2_f32 v[216:231], v121, v26, v[216:231]
	v_mfma_f32_32x32x2_f32 v[232:247], v121, v27, v[232:247]
	v_mfma_f32_32x32x2_f32 v[184:199], v122, v28, v[184:199]
	v_mfma_f32_32x32x2_f32 v[200:215], v122, v29, v[200:215]
	v_mfma_f32_32x32x2_f32 v[216:231], v122, v10, v[216:231]
	v_mfma_f32_32x32x2_f32 v[232:247], v122, v11, v[232:247]
	v_mfma_f32_32x32x2_f32 v[184:199], v123, v30, v[184:199]
	v_mfma_f32_32x32x2_f32 v[200:215], v123, v31, v[200:215]
	v_mfma_f32_32x32x2_f32 v[216:231], v123, v12, v[216:231]
	v_mfma_f32_32x32x2_f32 v[232:247], v123, v13, v[232:247]
	v_mfma_f32_32x32x2_f32 v[184:199], v124, v32, v[184:199]
	v_mfma_f32_32x32x2_f32 v[200:215], v124, v33, v[200:215]
	v_mfma_f32_32x32x2_f32 v[216:231], v124, v14, v[216:231]
	v_mfma_f32_32x32x2_f32 v[232:247], v124, v15, v[232:247]
	v_mfma_f32_32x32x2_f32 v[184:199], v125, v34, v[184:199]
	v_mfma_f32_32x32x2_f32 v[200:215], v125, v35, v[200:215]
	v_mfma_f32_32x32x2_f32 v[216:231], v125, v16, v[216:231]
	v_mfma_f32_32x32x2_f32 v[232:247], v125, v17, v[232:247]
	s_nop 18
	v_permlane32_swap_b32 v184, v216
	s_nop 18
	v_permlane32_swap_b32 v200, v232
	s_nop 16
	v_permlane32_swap_b32 v185, v217
	s_nop 16
	v_permlane32_swap_b32 v201, v233
	s_nop 14
	v_permlane32_swap_b32 v186, v218
	s_nop 14
	v_permlane32_swap_b32 v202, v234
	s_nop 12
	v_permlane32_swap_b32 v187, v219
	s_nop 12
	v_permlane32_swap_b32 v203, v235
	s_nop 10
	v_permlane32_swap_b32 v188, v220
	s_nop 10
	v_permlane32_swap_b32 v204, v236
	s_nop 8
	v_permlane32_swap_b32 v189, v221
	s_nop 8
	v_permlane32_swap_b32 v205, v237
	s_nop 6
	v_permlane32_swap_b32 v190, v222
	s_nop 6
	v_permlane32_swap_b32 v206, v238
	s_nop 4
	v_permlane32_swap_b32 v191, v223
	s_nop 4
	v_permlane32_swap_b32 v207, v239
	s_nop 2
	v_permlane32_swap_b32 v192, v224
	s_nop 2
	v_permlane32_swap_b32 v208, v240
	s_nop 0
	v_permlane32_swap_b32 v193, v225
	s_nop 0
	v_permlane32_swap_b32 v209, v241
	v_permlane32_swap_b32 v194, v226
	v_permlane32_swap_b32 v210, v242
	v_permlane32_swap_b32 v195, v227
	v_permlane32_swap_b32 v211, v243
	v_permlane32_swap_b32 v196, v228
	v_permlane32_swap_b32 v212, v244
	v_permlane32_swap_b32 v197, v229
	v_permlane32_swap_b32 v213, v245
	v_permlane32_swap_b32 v198, v230
	v_permlane32_swap_b32 v214, v246
	v_permlane32_swap_b32 v199, v231
	v_permlane32_swap_b32 v215, v247
	v_mul_f32_e32 v128, v23, v25
	v_mul_f32_e32 v129, v22, v25
	v_fma_f32 v130, v22, v24, -v128
	v_fma_f32 v131, v23, v24, v129
	v_add_f32_e32 v24, v130, v184
	v_add_f32_e32 v25, v131, v200
	v_mul_f32_e32 v128, v23, v25
	v_mul_f32_e32 v129, v22, v25
	v_fma_f32 v130, v22, v24, -v128
	v_fma_f32 v131, v23, v24, v129
	v_add_f32_e32 v24, v130, v185
	v_add_f32_e32 v25, v131, v201
	v_mul_f32_e32 v128, v23, v25
	v_mul_f32_e32 v129, v22, v25
	v_fma_f32 v130, v22, v24, -v128
	v_fma_f32 v131, v23, v24, v129
	v_add_f32_e32 v24, v130, v186
	v_add_f32_e32 v25, v131, v202
	v_mul_f32_e32 v128, v23, v25
	v_mul_f32_e32 v129, v22, v25
	v_fma_f32 v130, v22, v24, -v128
	v_fma_f32 v131, v23, v24, v129
	v_add_f32_e32 v24, v130, v187
	v_add_f32_e32 v25, v131, v203
	v_mul_f32_e32 v128, v23, v25
	v_mul_f32_e32 v129, v22, v25
	v_fma_f32 v130, v22, v24, -v128
	v_fma_f32 v131, v23, v24, v129
	v_add_f32_e32 v24, v130, v188
	v_add_f32_e32 v25, v131, v204
	v_mul_f32_e32 v128, v23, v25
	v_mul_f32_e32 v129, v22, v25
	v_fma_f32 v130, v22, v24, -v128
	v_fma_f32 v131, v23, v24, v129
	v_add_f32_e32 v24, v130, v189
	v_add_f32_e32 v25, v131, v205
	v_mul_f32_e32 v128, v23, v25
	v_mul_f32_e32 v129, v22, v25
	v_fma_f32 v130, v22, v24, -v128
	v_fma_f32 v131, v23, v24, v129
	v_add_f32_e32 v24, v130, v190
	v_add_f32_e32 v25, v131, v206
	v_mul_f32_e32 v128, v23, v25
	v_mul_f32_e32 v129, v22, v25
	v_fma_f32 v130, v22, v24, -v128
	v_fma_f32 v131, v23, v24, v129
	v_add_f32_e32 v24, v130, v191
	v_add_f32_e32 v25, v131, v207
	v_mul_f32_e32 v128, v23, v25
	v_mul_f32_e32 v129, v22, v25
	v_fma_f32 v130, v22, v24, -v128
	v_fma_f32 v131, v23, v24, v129
	v_add_f32_e32 v24, v130, v192
	v_add_f32_e32 v25, v131, v208
	v_mul_f32_e32 v128, v23, v25
	v_mul_f32_e32 v129, v22, v25
	v_fma_f32 v130, v22, v24, -v128
	v_fma_f32 v131, v23, v24, v129
	v_add_f32_e32 v24, v130, v193
	v_add_f32_e32 v25, v131, v209
	v_mul_f32_e32 v128, v23, v25
	v_mul_f32_e32 v129, v22, v25
	v_fma_f32 v130, v22, v24, -v128
	v_fma_f32 v131, v23, v24, v129
	v_add_f32_e32 v24, v130, v194
	v_add_f32_e32 v25, v131, v210
	v_mul_f32_e32 v128, v23, v25
	v_mul_f32_e32 v129, v22, v25
	v_fma_f32 v130, v22, v24, -v128
	v_fma_f32 v131, v23, v24, v129
	v_add_f32_e32 v24, v130, v195
	v_add_f32_e32 v25, v131, v211
	v_mul_f32_e32 v128, v23, v25
	v_mul_f32_e32 v129, v22, v25
	v_fma_f32 v130, v22, v24, -v128
	v_fma_f32 v131, v23, v24, v129
	v_add_f32_e32 v24, v130, v196
	v_add_f32_e32 v25, v131, v212
	v_mul_f32_e32 v128, v23, v25
	v_mul_f32_e32 v129, v22, v25
	v_fma_f32 v130, v22, v24, -v128
	v_fma_f32 v131, v23, v24, v129
; DI void ssm1_item(PREF p, int l, int item, unsigned char* ldsb) {
;     ...
;   for (int t = 0; t < 64; ++t) SSM_STEP(t)
	v_add_f32_e32 v24, v130, v197
	v_add_f32_e32 v25, v131, v213
	v_mul_f32_e32 v128, v23, v25
	v_mul_f32_e32 v129, v22, v25
	v_fma_f32 v130, v22, v24, -v128
	v_fma_f32 v131, v23, v24, v129
	v_add_f32_e32 v24, v130, v198
	v_add_f32_e32 v25, v131, v214
	v_mul_f32_e32 v128, v23, v25
	v_mul_f32_e32 v129, v22, v25
	v_fma_f32 v130, v22, v24, -v128
	v_fma_f32 v131, v23, v24, v129
	v_add_f32_e32 v24, v130, v199
	v_add_f32_e32 v25, v131, v215
	v_mul_f32_e32 v128, v23, v25
	v_mul_f32_e32 v129, v22, v25
	v_fma_f32 v130, v22, v24, -v128
	v_fma_f32 v131, v23, v24, v129
	v_add_f32_e32 v24, v130, v216
	v_add_f32_e32 v25, v131, v232
	v_mul_f32_e32 v128, v23, v25
	v_mul_f32_e32 v129, v22, v25
	v_fma_f32 v130, v22, v24, -v128
	v_fma_f32 v131, v23, v24, v129
	v_add_f32_e32 v24, v130, v217
	v_add_f32_e32 v25, v131, v233
	v_mul_f32_e32 v128, v23, v25
	v_mul_f32_e32 v129, v22, v25
	v_fma_f32 v130, v22, v24, -v128
	v_fma_f32 v131, v23, v24, v129
	v_add_f32_e32 v24, v130, v218
	v_add_f32_e32 v25, v131, v234
	v_mul_f32_e32 v128, v23, v25
	v_mul_f32_e32 v129, v22, v25
	v_fma_f32 v130, v22, v24, -v128
	v_fma_f32 v131, v23, v24, v129
	v_add_f32_e32 v24, v130, v219
	v_add_f32_e32 v25, v131, v235
	v_mul_f32_e32 v128, v23, v25
	v_mul_f32_e32 v129, v22, v25
	v_fma_f32 v130, v22, v24, -v128
	v_fma_f32 v131, v23, v24, v129
	v_add_f32_e32 v24, v130, v220
	v_add_f32_e32 v25, v131, v236
	v_mul_f32_e32 v128, v23, v25
	v_mul_f32_e32 v129, v22, v25
	v_fma_f32 v130, v22, v24, -v128
	v_fma_f32 v131, v23, v24, v129
	v_add_f32_e32 v24, v130, v221
	v_add_f32_e32 v25, v131, v237
	v_mul_f32_e32 v128, v23, v25
	v_mul_f32_e32 v129, v22, v25
	v_fma_f32 v130, v22, v24, -v128
	v_fma_f32 v131, v23, v24, v129
	v_add_f32_e32 v24, v130, v222
	v_add_f32_e32 v25, v131, v238
	v_mul_f32_e32 v128, v23, v25
	v_mul_f32_e32 v129, v22, v25
	v_fma_f32 v130, v22, v24, -v128
	v_fma_f32 v131, v23, v24, v129
	v_add_f32_e32 v24, v130, v223
	v_add_f32_e32 v25, v131, v239
	v_mul_f32_e32 v128, v23, v25
	v_mul_f32_e32 v129, v22, v25
	v_fma_f32 v130, v22, v24, -v128
	v_fma_f32 v131, v23, v24, v129
	v_add_f32_e32 v24, v130, v224
	v_add_f32_e32 v25, v131, v240
	v_mul_f32_e32 v128, v23, v25
	v_mul_f32_e32 v129, v22, v25
	v_fma_f32 v130, v22, v24, -v128
	v_fma_f32 v131, v23, v24, v129
	v_add_f32_e32 v24, v130, v225
	v_add_f32_e32 v25, v131, v241
	v_mul_f32_e32 v128, v23, v25
	v_mul_f32_e32 v129, v22, v25
	v_fma_f32 v130, v22, v24, -v128
	v_fma_f32 v131, v23, v24, v129
	v_add_f32_e32 v24, v130, v226
	v_add_f32_e32 v25, v131, v242
	v_mul_f32_e32 v128, v23, v25
	v_mul_f32_e32 v129, v22, v25
	v_fma_f32 v130, v22, v24, -v128
	v_fma_f32 v131, v23, v24, v129
	v_add_f32_e32 v24, v130, v227
	v_add_f32_e32 v25, v131, v243
	v_mul_f32_e32 v128, v23, v25
	v_mul_f32_e32 v129, v22, v25
	v_fma_f32 v130, v22, v24, -v128
	v_fma_f32 v131, v23, v24, v129
	v_add_f32_e32 v24, v130, v228
	v_add_f32_e32 v25, v131, v244
	v_mul_f32_e32 v128, v23, v25
	v_mul_f32_e32 v129, v22, v25
	v_fma_f32 v130, v22, v24, -v128
	v_fma_f32 v131, v23, v24, v129
	v_add_f32_e32 v24, v130, v229
	v_add_f32_e32 v25, v131, v245
	v_mul_f32_e32 v128, v23, v25
	v_mul_f32_e32 v129, v22, v25
	v_fma_f32 v130, v22, v24, -v128
	v_fma_f32 v131, v23, v24, v129
	v_add_f32_e32 v24, v130, v230
	v_add_f32_e32 v25, v131, v246
	v_mul_f32_e32 v128, v23, v25
	v_mul_f32_e32 v129, v22, v25
	v_fma_f32 v130, v22, v24, -v128
	v_fma_f32 v131, v23, v24, v129
	v_add_f32_e32 v24, v130, v231
	v_add_f32_e32 v25, v131, v247
	v_add_u32_e32 v127, 0x2000, v127
	ds_read2_b32 v[118:119], v127 offset0:0 offset1:2
	ds_read2_b32 v[120:121], v127 offset0:4 offset1:6
	ds_read2_b32 v[122:123], v127 offset0:8 offset1:10
	ds_read2_b32 v[124:125], v127 offset0:12 offset1:14
	s_waitcnt lgkmcnt(0)
	v_mfma_f32_32x32x2_f32 v[184:199], v118, v8, 0
	v_mfma_f32_32x32x2_f32 v[200:215], v118, v9, 0
	v_mfma_f32_32x32x2_f32 v[216:231], v118, v18, 0
	v_mfma_f32_32x32x2_f32 v[232:247], v118, v19, 0
	v_mfma_f32_32x32x2_f32 v[184:199], v119, v36, v[184:199]
	v_mfma_f32_32x32x2_f32 v[200:215], v119, v37, v[200:215]
	v_mfma_f32_32x32x2_f32 v[216:231], v119, v20, v[216:231]
	v_mfma_f32_32x32x2_f32 v[232:247], v119, v21, v[232:247]
	v_mfma_f32_32x32x2_f32 v[184:199], v120, v38, v[184:199]
	v_mfma_f32_32x32x2_f32 v[200:215], v120, v39, v[200:215]
	v_mfma_f32_32x32x2_f32 v[216:231], v120, v6, v[216:231]
	v_mfma_f32_32x32x2_f32 v[232:247], v120, v7, v[232:247]
	v_mfma_f32_32x32x2_f32 v[184:199], v121, v4, v[184:199]
	v_mfma_f32_32x32x2_f32 v[200:215], v121, v5, v[200:215]
	v_mfma_f32_32x32x2_f32 v[216:231], v121, v26, v[216:231]
	v_mfma_f32_32x32x2_f32 v[232:247], v121, v27, v[232:247]
	v_mfma_f32_32x32x2_f32 v[184:199], v122, v28, v[184:199]
	v_mfma_f32_32x32x2_f32 v[200:215], v122, v29, v[200:215]
	v_mfma_f32_32x32x2_f32 v[216:231], v122, v10, v[216:231]
	v_mfma_f32_32x32x2_f32 v[232:247], v122, v11, v[232:247]
	v_mfma_f32_32x32x2_f32 v[184:199], v123, v30, v[184:199]
	v_mfma_f32_32x32x2_f32 v[200:215], v123, v31, v[200:215]
	v_mfma_f32_32x32x2_f32 v[216:231], v123, v12, v[216:231]
	v_mfma_f32_32x32x2_f32 v[232:247], v123, v13, v[232:247]
	v_mfma_f32_32x32x2_f32 v[184:199], v124, v32, v[184:199]
	v_mfma_f32_32x32x2_f32 v[200:215], v124, v33, v[200:215]
	v_mfma_f32_32x32x2_f32 v[216:231], v124, v14, v[216:231]
	v_mfma_f32_32x32x2_f32 v[232:247], v124, v15, v[232:247]
	v_mfma_f32_32x32x2_f32 v[184:199], v125, v34, v[184:199]
	v_mfma_f32_32x32x2_f32 v[200:215], v125, v35, v[200:215]
	v_mfma_f32_32x32x2_f32 v[216:231], v125, v16, v[216:231]
	v_mfma_f32_32x32x2_f32 v[232:247], v125, v17, v[232:247]
	s_nop 18
	v_permlane32_swap_b32 v184, v216
	s_nop 18
	v_permlane32_swap_b32 v200, v232
	s_nop 16
	v_permlane32_swap_b32 v185, v217
; DI void ssm1_item(PREF p, int l, int item, unsigned char* ldsb) {
;     ...
;   for (int t = 0; t < 64; ++t) SSM_STEP(t)
	s_nop 16
	v_permlane32_swap_b32 v201, v233
	s_nop 14
	v_permlane32_swap_b32 v186, v218
	s_nop 14
	v_permlane32_swap_b32 v202, v234
	s_nop 12
	v_permlane32_swap_b32 v187, v219
	s_nop 12
	v_permlane32_swap_b32 v203, v235
	s_nop 10
	v_permlane32_swap_b32 v188, v220
	s_nop 10
	v_permlane32_swap_b32 v204, v236
	s_nop 8
	v_permlane32_swap_b32 v189, v221
	s_nop 8
	v_permlane32_swap_b32 v205, v237
	s_nop 6
	v_permlane32_swap_b32 v190, v222
	s_nop 6
	v_permlane32_swap_b32 v206, v238
	s_nop 4
	v_permlane32_swap_b32 v191, v223
	s_nop 4
	v_permlane32_swap_b32 v207, v239
	s_nop 2
	v_permlane32_swap_b32 v192, v224
	s_nop 2
	v_permlane32_swap_b32 v208, v240
	s_nop 0
	v_permlane32_swap_b32 v193, v225
	s_nop 0
	v_permlane32_swap_b32 v209, v241
	v_permlane32_swap_b32 v194, v226
	v_permlane32_swap_b32 v210, v242
	v_permlane32_swap_b32 v195, v227
	v_permlane32_swap_b32 v211, v243
	v_permlane32_swap_b32 v196, v228
	v_permlane32_swap_b32 v212, v244
	v_permlane32_swap_b32 v197, v229
	v_permlane32_swap_b32 v213, v245
	v_permlane32_swap_b32 v198, v230
	v_permlane32_swap_b32 v214, v246
	v_permlane32_swap_b32 v199, v231
	v_permlane32_swap_b32 v215, v247
	v_mul_f32_e32 v128, v23, v25
	v_mul_f32_e32 v129, v22, v25
	v_fma_f32 v130, v22, v24, -v128
	v_fma_f32 v131, v23, v24, v129
	v_add_f32_e32 v24, v130, v184
	v_add_f32_e32 v25, v131, v200
	v_mul_f32_e32 v128, v23, v25
	v_mul_f32_e32 v129, v22, v25
	v_fma_f32 v130, v22, v24, -v128
	v_fma_f32 v131, v23, v24, v129
	v_add_f32_e32 v24, v130, v185
	v_add_f32_e32 v25, v131, v201
	v_mul_f32_e32 v128, v23, v25
	v_mul_f32_e32 v129, v22, v25
	v_fma_f32 v130, v22, v24, -v128
	v_fma_f32 v131, v23, v24, v129
	v_add_f32_e32 v24, v130, v186
	v_add_f32_e32 v25, v131, v202
	v_mul_f32_e32 v128, v23, v25
	v_mul_f32_e32 v129, v22, v25
	v_fma_f32 v130, v22, v24, -v128
	v_fma_f32 v131, v23, v24, v129
	v_add_f32_e32 v24, v130, v187
	v_add_f32_e32 v25, v131, v203
	v_mul_f32_e32 v128, v23, v25
	v_mul_f32_e32 v129, v22, v25
	v_fma_f32 v130, v22, v24, -v128
	v_fma_f32 v131, v23, v24, v129
	v_add_f32_e32 v24, v130, v188
	v_add_f32_e32 v25, v131, v204
	v_mul_f32_e32 v128, v23, v25
	v_mul_f32_e32 v129, v22, v25
	v_fma_f32 v130, v22, v24, -v128
	v_fma_f32 v131, v23, v24, v129
	v_add_f32_e32 v24, v130, v189
	v_add_f32_e32 v25, v131, v205
	v_mul_f32_e32 v128, v23, v25
	v_mul_f32_e32 v129, v22, v25
	v_fma_f32 v130, v22, v24, -v128
	v_fma_f32 v131, v23, v24, v129
	v_add_f32_e32 v24, v130, v190
	v_add_f32_e32 v25, v131, v206
	v_mul_f32_e32 v128, v23, v25
	v_mul_f32_e32 v129, v22, v25
	v_fma_f32 v130, v22, v24, -v128
	v_fma_f32 v131, v23, v24, v129
	v_add_f32_e32 v24, v130, v191
	v_add_f32_e32 v25, v131, v207
	v_mul_f32_e32 v128, v23, v25
	v_mul_f32_e32 v129, v22, v25
	v_fma_f32 v130, v22, v24, -v128
	v_fma_f32 v131, v23, v24, v129
	v_add_f32_e32 v24, v130, v192
	v_add_f32_e32 v25, v131, v208
	v_mul_f32_e32 v128, v23, v25
	v_mul_f32_e32 v129, v22, v25
	v_fma_f32 v130, v22, v24, -v128
	v_fma_f32 v131, v23, v24, v129
	v_add_f32_e32 v24, v130, v193
	v_add_f32_e32 v25, v131, v209
	v_mul_f32_e32 v128, v23, v25
	v_mul_f32_e32 v129, v22, v25
	v_fma_f32 v130, v22, v24, -v128
	v_fma_f32 v131, v23, v24, v129
	v_add_f32_e32 v24, v130, v194
	v_add_f32_e32 v25, v131, v210
	v_mul_f32_e32 v128, v23, v25
	v_mul_f32_e32 v129, v22, v25
	v_fma_f32 v130, v22, v24, -v128
	v_fma_f32 v131, v23, v24, v129
	v_add_f32_e32 v24, v130, v195
	v_add_f32_e32 v25, v131, v211
	v_mul_f32_e32 v128, v23, v25
	v_mul_f32_e32 v129, v22, v25
	v_fma_f32 v130, v22, v24, -v128
	v_fma_f32 v131, v23, v24, v129
	v_add_f32_e32 v24, v130, v196
	v_add_f32_e32 v25, v131, v212
	v_mul_f32_e32 v128, v23, v25
	v_mul_f32_e32 v129, v22, v25
	v_fma_f32 v130, v22, v24, -v128
	v_fma_f32 v131, v23, v24, v129
	v_add_f32_e32 v24, v130, v197
	v_add_f32_e32 v25, v131, v213
	v_mul_f32_e32 v128, v23, v25
	v_mul_f32_e32 v129, v22, v25
; DI int tidx() { int t = threadIdx.x & 255; asm volatile("" : "+v"(t)); return t; }
; DI int vbid() { return (int)blockIdx.x * 2 + half_(); }
; DI int vgrid() { return (int)gridDim.x * 2; }
; DI void ssm1_item(PREF p, int l, int item, unsigned char* ldsb) {
;   const int gq = item & 3, c = (item >> 2) & 63, b = item >> 8;
;   const int tid = tidx(), w = tid >> 6, lane = tid & 63;
;   const int g = gq * 4 + w;
;   float* uS = (float*)ldsb;
;   __syncthreads();
;   ssm_stage_u(p, b, c, gq, uS);
;   __syncthreads();
;   const size_t pi = (size_t)(l * 16 + g) * 64 + lane;
;   float bre[16], bim[16];
; #pragma unroll
;   for (int j = 0; j < 16; ++j) { bre[j] = p.bbre[pi * 16 + j]; bim[j] = p.bbim[pi * 16 + j]; }
;   const float lr = p.lam[pi * 2], li = p.lam[pi * 2 + 1];
;   float hr = 0.f, hi = 0.f;
;   for (int t = 0; t < 64; ++t) SSM_STEP(t)
;   ((float2*)p.hend)[((size_t)(b * 16 + g) * 64 + c) * 64 + lane] = make_float2(hr, hi);
; DI void phase_mix1(PREF p, int l, unsigned char* ldsb) {
;     ...
;   for (int it = vbid(); it < 2048; it += vgrid()) ssm1_item(p, l, it, ldsb);
	v_fma_f32 v130, v22, v24, -v128
	v_fma_f32 v131, v23, v24, v129
	v_add_f32_e32 v24, v130, v198
	v_add_f32_e32 v25, v131, v214
	v_mul_f32_e32 v128, v23, v25
	v_mul_f32_e32 v129, v22, v25
	v_fma_f32 v130, v22, v24, -v128
	v_fma_f32 v131, v23, v24, v129
	v_add_f32_e32 v24, v130, v199
	v_add_f32_e32 v25, v131, v215
	v_mul_f32_e32 v128, v23, v25
	v_mul_f32_e32 v129, v22, v25
	v_fma_f32 v130, v22, v24, -v128
	v_fma_f32 v131, v23, v24, v129
	v_add_f32_e32 v24, v130, v216
	v_add_f32_e32 v25, v131, v232
	v_mul_f32_e32 v128, v23, v25
	v_mul_f32_e32 v129, v22, v25
	v_fma_f32 v130, v22, v24, -v128
	v_fma_f32 v131, v23, v24, v129
	v_add_f32_e32 v24, v130, v217
	v_add_f32_e32 v25, v131, v233
	v_mul_f32_e32 v128, v23, v25
	v_mul_f32_e32 v129, v22, v25
	v_fma_f32 v130, v22, v24, -v128
	v_fma_f32 v131, v23, v24, v129
	v_add_f32_e32 v24, v130, v218
	v_add_f32_e32 v25, v131, v234
	v_mul_f32_e32 v128, v23, v25
	v_mul_f32_e32 v129, v22, v25
	v_fma_f32 v130, v22, v24, -v128
	v_fma_f32 v131, v23, v24, v129
	v_add_f32_e32 v24, v130, v219
	v_add_f32_e32 v25, v131, v235
	v_mul_f32_e32 v128, v23, v25
	v_mul_f32_e32 v129, v22, v25
	v_fma_f32 v130, v22, v24, -v128
	v_fma_f32 v131, v23, v24, v129
	v_add_f32_e32 v24, v130, v220
	v_add_f32_e32 v25, v131, v236
	v_mul_f32_e32 v128, v23, v25
	v_mul_f32_e32 v129, v22, v25
	v_fma_f32 v130, v22, v24, -v128
	v_fma_f32 v131, v23, v24, v129
	v_add_f32_e32 v24, v130, v221
	v_add_f32_e32 v25, v131, v237
	v_mul_f32_e32 v128, v23, v25
	v_mul_f32_e32 v129, v22, v25
	v_fma_f32 v130, v22, v24, -v128
	v_fma_f32 v131, v23, v24, v129
	v_add_f32_e32 v24, v130, v222
	v_add_f32_e32 v25, v131, v238
	v_mul_f32_e32 v128, v23, v25
	v_mul_f32_e32 v129, v22, v25
	v_fma_f32 v130, v22, v24, -v128
	v_fma_f32 v131, v23, v24, v129
	v_add_f32_e32 v24, v130, v223
	v_add_f32_e32 v25, v131, v239
	v_mul_f32_e32 v128, v23, v25
	v_mul_f32_e32 v129, v22, v25
	v_fma_f32 v130, v22, v24, -v128
	v_fma_f32 v131, v23, v24, v129
	v_add_f32_e32 v24, v130, v224
	v_add_f32_e32 v25, v131, v240
	v_mul_f32_e32 v128, v23, v25
	v_mul_f32_e32 v129, v22, v25
	v_fma_f32 v130, v22, v24, -v128
	v_fma_f32 v131, v23, v24, v129
	v_add_f32_e32 v24, v130, v225
	v_add_f32_e32 v25, v131, v241
	v_mul_f32_e32 v128, v23, v25
	v_mul_f32_e32 v129, v22, v25
	v_fma_f32 v130, v22, v24, -v128
	v_fma_f32 v131, v23, v24, v129
	v_add_f32_e32 v24, v130, v226
	v_add_f32_e32 v25, v131, v242
	v_mul_f32_e32 v128, v23, v25
	v_mul_f32_e32 v129, v22, v25
	v_fma_f32 v130, v22, v24, -v128
	v_fma_f32 v131, v23, v24, v129
	v_add_f32_e32 v24, v130, v227
	v_add_f32_e32 v25, v131, v243
	v_mul_f32_e32 v128, v23, v25
	v_mul_f32_e32 v129, v22, v25
	v_fma_f32 v130, v22, v24, -v128
	v_fma_f32 v131, v23, v24, v129
	v_add_f32_e32 v24, v130, v228
	v_add_f32_e32 v25, v131, v244
	v_mul_f32_e32 v128, v23, v25
	v_mul_f32_e32 v129, v22, v25
	v_fma_f32 v130, v22, v24, -v128
	v_fma_f32 v131, v23, v24, v129
	v_add_f32_e32 v24, v130, v229
	v_add_f32_e32 v25, v131, v245
	v_mul_f32_e32 v128, v23, v25
	v_mul_f32_e32 v129, v22, v25
	v_fma_f32 v130, v22, v24, -v128
	v_fma_f32 v131, v23, v24, v129
	v_add_f32_e32 v24, v130, v230
	v_add_f32_e32 v25, v131, v246
	v_mul_f32_e32 v128, v23, v25
	v_mul_f32_e32 v129, v22, v25
	v_fma_f32 v130, v22, v24, -v128
	v_fma_f32 v131, v23, v24, v129
	v_add_f32_e32 v24, v130, v231
	v_add_f32_e32 v25, v131, v247
	v_readlane_b32 s18, v254, 46
	v_readlane_b32 s19, v254, 47
	s_load_dwordx2 s[0:1], s[18:19], 0x188
	v_lshl_add_u32 v2, s14, 4, v41
	v_ashrrev_i32_e32 v3, 31, v2
	v_lshlrev_b64 v[2:3], 15, v[2:3]
	s_lshl_b32 s52, s15, 3
	s_waitcnt lgkmcnt(0)
	v_lshl_add_u64 v[2:3], s[0:1], 0, v[2:3]
	v_lshl_add_u64 v[2:3], v[2:3], 0, s[52:53]
	v_lshlrev_b32_e32 v0, 3, v0
	s_add_i32 s12, s12, s99
	v_lshl_add_u64 v[2:3], v[2:3], 0, v[0:1]
	s_cmp_gt_i32 s12, s98
	global_store_dwordx2 v[2:3], v[24:25], off
	s_cbranch_scc0 .LBB0_422
